# v26 plus hand-written epilogue for the half retention unit: LDS transpose, 16-byte gate loads and stores instead of 2-byte ones
# baseline (speedup 1.0000x reference)
.LBB0_388:
	s_barrier
	s_waitcnt vmcnt(3)
	ds_write_b128 v82, v[50:53]
	s_waitcnt vmcnt(2)
	ds_write_b128 v82, v[54:57] offset:17408
	s_waitcnt vmcnt(1)
	ds_write_b128 v80, v[58:61]
	s_waitcnt vmcnt(0)
	ds_write_b128 v80, v[62:65] offset:17408
	s_waitcnt lgkmcnt(0)
	s_barrier
	ds_read_b128 v[116:119], v83
	ds_read_b128 v[74:77], v83 offset:64
	ds_read_b128 v[70:73], v83 offset:128
	ds_read_b128 v[66:69], v83 offset:192
	s_waitcnt lgkmcnt(3)
	v_mfma_f32_16x16x32_bf16 v[116:119], v[116:119], v[30:33], 0
	v_add_u32_e32 v56, s63, v103
	v_add_u32_e32 v120, s62, v101
	v_cvt_f32_i32_e32 v122, v56
	s_waitcnt lgkmcnt(2)
	v_mfma_f32_16x16x32_bf16 v[74:77], v[74:77], v[22:25], v[116:119]
	v_cvt_f32_i32_e32 v121, v120
	v_lshl_add_u64 v[50:51], v[88:89], 0, v[84:85]
	v_mul_f32_e32 v122, v99, v122
	s_waitcnt lgkmcnt(1)
	v_mfma_f32_16x16x32_bf16 v[70:73], v[70:73], v[14:17], v[74:77]
	v_add_co_u32_e32 v54, vcc, s5, v50
	v_mul_f32_e32 v121, v90, v121
	v_exp_f32_e32 v122, v122
	v_lshl_add_u64 v[52:53], v[86:87], 0, v[84:85]
	v_addc_co_u32_e32 v55, vcc, 0, v51, vcc
	v_exp_f32_e32 v121, v121
	v_add_co_u32_e32 v62, vcc, s5, v52
	s_waitcnt lgkmcnt(0)
	v_mfma_f32_16x16x32_bf16 v[66:69], v[66:69], v[10:13], v[70:73]
	v_addc_co_u32_e32 v63, vcc, 0, v53, vcc
	v_mul_f32_e32 v133, v98, v122
	v_mul_f32_e32 v135, v96, v122
	v_cmp_ne_u32_e32 vcc, s62, v115
	v_cmp_gt_i32_e64 s[10:11], 0, v120
	v_mul_f32_e32 v132, v97, v121
	v_mul_f32_e32 v134, v95, v121
	v_mul_f32_e32 v137, v94, v122
	v_cmp_ne_u32_e64 s[6:7], s62, v114
	v_mul_f32_e32 v122, v92, v122
	v_cmp_ne_u32_e64 s[8:9], s62, v113
	v_cndmask_b32_e64 v133, 2.0, v133, s[10:11]
	v_cndmask_b32_e32 v135, 2.0, v135, vcc
	v_cmp_lt_i32_e32 vcc, 1, v120
	v_cmp_lt_i32_e64 s[36:37], 0, v120
	v_add_u32_e32 v123, -16, v120
	v_subrev_u32_e32 v125, 32, v120
	v_subrev_u32_e32 v127, 48, v120
	v_mul_f32_e32 v136, v93, v121
	v_mul_f32_e32 v121, v91, v121
	v_cndmask_b32_e64 v137, 2.0, v137, s[6:7]
	v_cmp_lt_i32_e64 s[6:7], 2, v120
	v_cndmask_b32_e64 v122, 2.0, v122, s[8:9]
	v_cmp_lt_i32_e64 s[8:9], 3, v120
	v_cndmask_b32_e64 v120, v133, v132, s[36:37]
	v_cndmask_b32_e32 v132, v135, v134, vcc
	v_cndmask_b32_e64 v133, v137, v136, s[6:7]
	v_cndmask_b32_e64 v121, v122, v121, s[8:9]
	v_mul_f32_e32 v66, v120, v66
	v_mul_f32_e32 v67, v132, v67
	v_add_u32_e32 v124, 16, v56
	v_add_u32_e32 v126, 32, v56
	v_add_u32_e32 v128, 48, v56
	global_load_dwordx4 v[50:53], v[54:55], off offset:1024
	s_nop 0
	global_load_dwordx4 v[54:57], v[54:55], off offset:2048
	s_nop 0
	global_load_dwordx4 v[58:61], v[62:63], off offset:1024
	s_nop 0
	global_load_dwordx4 v[62:65], v[62:63], off offset:2048
	v_mul_f32_e32 v68, v133, v68
	v_mul_f32_e32 v69, v121, v69
	v_cvt_pk_bf16_f32 v66, v66, v67
	v_cvt_pk_bf16_f32 v67, v68, v69
	ds_write_b64 v100, v[66:67] offset:53248
	ds_read_b128 v[66:69], v83 offset:4352
	ds_read_b128 v[70:73], v83 offset:4416
	s_waitcnt lgkmcnt(1)
	v_mfma_f32_16x16x32_bf16 v[66:69], v[66:69], v[30:33], 0
	ds_read_b128 v[74:77], v83 offset:4480
	v_cvt_f32_i32_e32 v124, v124
	v_cvt_f32_i32_e32 v129, v123
	s_waitcnt lgkmcnt(1)
	v_mfma_f32_16x16x32_bf16 v[66:69], v[70:73], v[22:25], v[66:69]
	ds_read_b128 v[70:73], v83 offset:4544
	v_mul_f32_e32 v124, v99, v124
	v_mul_f32_e32 v129, v90, v129
	s_waitcnt lgkmcnt(1)
	v_mfma_f32_16x16x32_bf16 v[66:69], v[74:77], v[14:17], v[66:69]
	v_exp_f32_e32 v124, v124
	v_exp_f32_e32 v129, v129
	v_cmp_gt_i32_e64 s[10:11], 0, v123
	s_waitcnt lgkmcnt(0)
	v_mfma_f32_16x16x32_bf16 v[66:69], v[70:73], v[10:13], v[66:69]
	v_mul_f32_e32 v139, v98, v124
	v_mul_f32_e32 v141, v96, v124
	v_cmp_ne_u32_e64 s[12:13], s62, v110
	v_mul_f32_e32 v138, v97, v129
	v_mul_f32_e32 v140, v95, v129
	v_mul_f32_e32 v143, v94, v124
	v_cmp_ne_u32_e64 s[14:15], s62, v111
	v_mul_f32_e32 v124, v92, v124
	v_cmp_ne_u32_e64 s[16:17], s62, v112
	v_cndmask_b32_e64 v122, 2.0, v139, s[10:11]
	v_cmp_lt_i32_e32 vcc, 0, v123
	v_cndmask_b32_e64 v134, 2.0, v141, s[12:13]
	v_cmp_lt_i32_e64 s[6:7], 1, v123
	v_mul_f32_e32 v142, v93, v129
	v_mul_f32_e32 v129, v91, v129
	v_cndmask_b32_e64 v135, 2.0, v143, s[14:15]
	v_cmp_lt_i32_e64 s[8:9], 2, v123
	v_cndmask_b32_e64 v124, 2.0, v124, s[16:17]
	v_cmp_lt_i32_e64 s[10:11], 3, v123
	v_cndmask_b32_e32 v117, v122, v138, vcc
	v_cndmask_b32_e64 v118, v134, v140, s[6:7]
	v_cndmask_b32_e64 v119, v135, v142, s[8:9]
	v_cndmask_b32_e64 v74, v124, v129, s[10:11]
	v_mul_f32_e32 v66, v117, v66
	v_mul_f32_e32 v67, v118, v67
	v_mul_f32_e32 v68, v119, v68
	v_mul_f32_e32 v69, v74, v69
	v_cvt_pk_bf16_f32 v66, v66, v67
	v_cvt_pk_bf16_f32 v67, v68, v69
	ds_write_b64 v100, v[66:67] offset:53280
	ds_read_b128 v[66:69], v83 offset:8704
	ds_read_b128 v[70:73], v83 offset:8768
	s_waitcnt lgkmcnt(1)
	v_mfma_f32_16x16x32_bf16 v[66:69], v[66:69], v[30:33], 0
	ds_read_b128 v[74:77], v83 offset:8832
	v_cvt_f32_i32_e32 v126, v126
	v_cvt_f32_i32_e32 v130, v125
	s_waitcnt lgkmcnt(1)
	v_mfma_f32_16x16x32_bf16 v[66:69], v[70:73], v[22:25], v[66:69]
	ds_read_b128 v[70:73], v83 offset:8896
	v_mul_f32_e32 v126, v99, v126
	v_mul_f32_e32 v130, v90, v130
	s_waitcnt lgkmcnt(1)
	v_mfma_f32_16x16x32_bf16 v[66:69], v[74:77], v[14:17], v[66:69]
	v_exp_f32_e32 v126, v126
	v_exp_f32_e32 v130, v130
	v_cmp_gt_i32_e64 s[18:19], 0, v125
	s_waitcnt lgkmcnt(0)
	v_mfma_f32_16x16x32_bf16 v[66:69], v[70:73], v[10:13], v[66:69]
	v_mul_f32_e32 v145, v98, v126
	v_mul_f32_e32 v147, v96, v126
	v_cmp_ne_u32_e64 s[20:21], s62, v107
	v_mul_f32_e32 v144, v97, v130
	v_mul_f32_e32 v146, v95, v130
	v_mul_f32_e32 v149, v94, v126
	v_cmp_ne_u32_e64 s[22:23], s62, v108
	v_mul_f32_e32 v126, v92, v126
	v_cmp_ne_u32_e64 s[24:25], s62, v109
	v_cndmask_b32_e64 v123, 2.0, v145, s[18:19]
	v_cmp_lt_i32_e64 s[12:13], 0, v125
	v_cndmask_b32_e64 v136, 2.0, v147, s[20:21]
	v_cmp_lt_i32_e64 s[14:15], 1, v125
	v_mul_f32_e32 v148, v93, v130
	v_mul_f32_e32 v130, v91, v130
	v_cndmask_b32_e64 v137, 2.0, v149, s[22:23]
	v_cmp_lt_i32_e64 s[16:17], 2, v125
	v_cndmask_b32_e64 v126, 2.0, v126, s[24:25]
	v_cmp_lt_i32_e64 s[18:19], 3, v125
	v_cndmask_b32_e64 v120, v123, v144, s[12:13]
	v_cndmask_b32_e64 v121, v136, v146, s[14:15]
	v_cndmask_b32_e64 v74, v137, v148, s[16:17]
	v_cndmask_b32_e64 v75, v126, v130, s[18:19]
	v_mul_f32_e32 v66, v120, v66
	v_mul_f32_e32 v67, v121, v67
	v_mul_f32_e32 v68, v74, v68
	v_mul_f32_e32 v69, v75, v69
	v_cvt_pk_bf16_f32 v66, v66, v67
	v_cvt_pk_bf16_f32 v67, v68, v69
	ds_write_b64 v100, v[66:67] offset:53312
	ds_read_b128 v[66:69], v83 offset:13056
	ds_read_b128 v[70:73], v83 offset:13120
	s_waitcnt lgkmcnt(1)
	v_mfma_f32_16x16x32_bf16 v[66:69], v[66:69], v[30:33], 0
	ds_read_b128 v[74:77], v83 offset:13184
	v_cvt_f32_i32_e32 v128, v128
	v_cvt_f32_i32_e32 v131, v127
	s_waitcnt lgkmcnt(1)
	v_mfma_f32_16x16x32_bf16 v[66:69], v[70:73], v[22:25], v[66:69]
	ds_read_b128 v[70:73], v83 offset:13248
	v_mul_f32_e32 v128, v99, v128
	v_mul_f32_e32 v131, v90, v131
	s_waitcnt lgkmcnt(1)
	v_mfma_f32_16x16x32_bf16 v[66:69], v[74:77], v[14:17], v[66:69]
	v_exp_f32_e32 v128, v128
	v_exp_f32_e32 v131, v131
	v_cmp_gt_i32_e64 s[26:27], 0, v127
	s_waitcnt lgkmcnt(0)
	v_mfma_f32_16x16x32_bf16 v[66:69], v[70:73], v[10:13], v[66:69]
	v_mul_f32_e32 v151, v98, v128
	v_mul_f32_e32 v153, v96, v128
	v_cmp_ne_u32_e64 s[28:29], s62, v104
	v_mul_f32_e32 v150, v97, v131
	v_mul_f32_e32 v152, v95, v131
	v_mul_f32_e32 v155, v94, v128
	v_cmp_ne_u32_e64 s[30:31], s62, v105
	v_mul_f32_e32 v128, v92, v128
	v_cmp_ne_u32_e64 s[34:35], s62, v106
	v_cndmask_b32_e64 v125, 2.0, v151, s[26:27]
	v_cmp_lt_i32_e64 s[20:21], 0, v127
	v_cndmask_b32_e64 v139, 2.0, v153, s[28:29]
	v_cmp_lt_i32_e64 s[22:23], 1, v127
	v_mul_f32_e32 v154, v93, v131
	v_mul_f32_e32 v131, v91, v131
	v_cndmask_b32_e64 v141, 2.0, v155, s[30:31]
	v_cmp_lt_i32_e64 s[24:25], 2, v127
	v_cndmask_b32_e64 v116, 2.0, v128, s[34:35]
	v_cmp_lt_i32_e64 s[26:27], 3, v127
	v_cndmask_b32_e64 v117, v125, v150, s[20:21]
	v_cndmask_b32_e64 v74, v139, v152, s[22:23]
	v_cndmask_b32_e64 v75, v141, v154, s[24:25]
	v_cndmask_b32_e64 v76, v116, v131, s[26:27]
	v_mul_f32_e32 v66, v117, v66
	v_mul_f32_e32 v67, v74, v67
	v_mul_f32_e32 v68, v75, v68
	v_mul_f32_e32 v69, v76, v69
	v_cvt_pk_bf16_f32 v66, v66, v67
	v_cvt_pk_bf16_f32 v67, v68, v69
	ds_write_b64 v100, v[66:67] offset:53344
	v_add_u32_e32 v79, v102, v78
	s_waitcnt lgkmcnt(0)
	ds_read_b128 v[66:69], v79 offset:53248
	ds_read_b128 v[70:73], v79 offset:53312
	ds_read_b64_tr_b16 v[76:77], v81 offset:18496
	ds_read_b64_tr_b16 v[74:75], v81 offset:17408
	ds_read_b64_tr_b16 v[116:117], v81 offset:17440
	ds_read_b64_tr_b16 v[120:121], v81 offset:17472
	ds_read_b64_tr_b16 v[124:125], v81 offset:17504
	ds_read_b64_tr_b16 v[118:119], v81 offset:18528
	ds_read_b64_tr_b16 v[122:123], v81 offset:18560
	ds_read_b64_tr_b16 v[126:127], v81 offset:18592
	s_waitcnt lgkmcnt(6)
	v_mfma_f32_16x16x32_bf16 v[46:49], v[66:69], v[74:77], v[46:49]
	ds_read_b64_tr_b16 v[74:75], v81 offset:17536
	ds_read_b64_tr_b16 v[76:77], v81 offset:18624
	s_add_i32 s63, s63, 64
	s_sub_i32 s62, s62, 64
	s_waitcnt lgkmcnt(4)
	v_mfma_f32_16x16x32_bf16 v[42:45], v[66:69], v[116:119], v[42:45]
	v_lshl_add_u64 v[86:87], v[86:87], 0, s[64:65]
	s_cmpk_eq_i32 s62, 0xff40
	v_lshl_add_u64 v[88:89], v[88:89], 0, s[64:65]
	s_waitcnt lgkmcnt(3)
	v_mfma_f32_16x16x32_bf16 v[38:41], v[66:69], v[120:123], v[38:41]
	ds_read_b64_tr_b16 v[116:117], v81 offset:17568
	ds_read_b64_tr_b16 v[120:121], v81 offset:17600
	ds_read_b64_tr_b16 v[128:129], v81 offset:17632
	ds_read_b64_tr_b16 v[118:119], v81 offset:18656
	ds_read_b64_tr_b16 v[122:123], v81 offset:18688
	ds_read_b64_tr_b16 v[130:131], v81 offset:18720
	s_waitcnt lgkmcnt(6)
	v_mfma_f32_16x16x32_bf16 v[26:29], v[66:69], v[74:77], v[26:29]
	ds_read_b64_tr_b16 v[74:75], v81 offset:26112
	ds_read_b64_tr_b16 v[76:77], v81 offset:27200
	v_mfma_f32_16x16x32_bf16 v[34:37], v[66:69], v[124:127], v[34:37]
	s_waitcnt lgkmcnt(4)
	v_mfma_f32_16x16x32_bf16 v[18:21], v[66:69], v[116:119], v[18:21]
	s_waitcnt lgkmcnt(3)
	v_mfma_f32_16x16x32_bf16 v[2:5], v[66:69], v[120:123], v[2:5]
	ds_read_b64_tr_b16 v[116:117], v81 offset:26144
	ds_read_b64_tr_b16 v[120:121], v81 offset:26176
	ds_read_b64_tr_b16 v[124:125], v81 offset:26208
	ds_read_b64_tr_b16 v[118:119], v81 offset:27232
	ds_read_b64_tr_b16 v[122:123], v81 offset:27264
	ds_read_b64_tr_b16 v[126:127], v81 offset:27296
	s_waitcnt lgkmcnt(8)
	v_mfma_f32_16x16x32_bf16 v[6:9], v[66:69], v[128:131], v[6:9]
	ds_read_b64_tr_b16 v[66:67], v81 offset:26240
	ds_read_b64_tr_b16 v[68:69], v81 offset:27328
	s_waitcnt lgkmcnt(8)
	v_mfma_f32_16x16x32_bf16 v[46:49], v[70:73], v[74:77], v[46:49]
	s_waitcnt lgkmcnt(4)
	v_mfma_f32_16x16x32_bf16 v[42:45], v[70:73], v[116:119], v[42:45]
	s_waitcnt lgkmcnt(3)
	v_mfma_f32_16x16x32_bf16 v[38:41], v[70:73], v[120:123], v[38:41]
	ds_read_b64_tr_b16 v[74:75], v81 offset:26272
	ds_read_b64_tr_b16 v[116:117], v81 offset:26304
	ds_read_b64_tr_b16 v[120:121], v81 offset:26336
	ds_read_b64_tr_b16 v[76:77], v81 offset:27360
	ds_read_b64_tr_b16 v[118:119], v81 offset:27392
	ds_read_b64_tr_b16 v[122:123], v81 offset:27424
	s_waitcnt lgkmcnt(8)
	v_mfma_f32_16x16x32_bf16 v[34:37], v[70:73], v[124:127], v[34:37]
	s_waitcnt lgkmcnt(6)
	v_mfma_f32_16x16x32_bf16 v[26:29], v[70:73], v[66:69], v[26:29]
	s_waitcnt lgkmcnt(2)
	v_mfma_f32_16x16x32_bf16 v[18:21], v[70:73], v[74:77], v[18:21]
	s_waitcnt lgkmcnt(1)
	v_mfma_f32_16x16x32_bf16 v[2:5], v[70:73], v[116:119], v[2:5]
	s_waitcnt lgkmcnt(0)
	v_mfma_f32_16x16x32_bf16 v[6:9], v[70:73], v[120:123], v[6:9]
	s_cbranch_scc0 .LBB0_388
	s_barrier
	s_waitcnt vmcnt(3)
	ds_write_b128 v82, v[50:53]
	s_waitcnt vmcnt(2)
	ds_write_b128 v82, v[54:57] offset:17408
	s_waitcnt vmcnt(1)
	ds_write_b128 v80, v[58:61]
	s_waitcnt vmcnt(0)
	ds_write_b128 v80, v[62:65] offset:17408
	s_waitcnt lgkmcnt(0)
	s_barrier
	ds_read_b128 v[50:53], v83
	ds_read_b128 v[54:57], v83 offset:64
	ds_read_b128 v[58:61], v83 offset:128
	ds_read_b128 v[62:65], v83 offset:192
	s_waitcnt lgkmcnt(3)
	v_mfma_f32_16x16x32_bf16 v[50:53], v[50:53], v[30:33], 0
	v_sub_u32_e32 v67, 0xc0, v101
	v_add_u32_e32 v66, 0xffffff40, v101
	v_cvt_f32_i32_e32 v66, v66
	s_waitcnt lgkmcnt(2)
	v_mfma_f32_16x16x32_bf16 v[50:53], v[54:57], v[22:25], v[50:53]
	v_cvt_f32_i32_e32 v54, v67
	s_movk_i32 s5, 0xc0
	v_mul_f32_e32 v55, v90, v66
	s_waitcnt lgkmcnt(1)
	v_mfma_f32_16x16x32_bf16 v[50:53], v[58:61], v[14:17], v[50:53]
	v_mul_f32_e32 v54, v99, v54
	v_exp_f32_e32 v54, v54
	v_exp_f32_e32 v55, v55
	s_waitcnt lgkmcnt(0)
	v_mfma_f32_16x16x32_bf16 v[50:53], v[62:65], v[10:13], v[50:53]
	v_cmp_ne_u32_e32 vcc, s5, v101
	v_mul_f32_e32 v57, v54, v98
	v_mul_f32_e32 v56, v55, v97
	v_cndmask_b32_e32 v57, 2.0, v57, vcc
	v_cmp_lt_i32_e32 vcc, s5, v101
	s_movk_i32 s5, 0xc1
	v_sub_u32_e32 v67, 0xd0, v101
	v_cndmask_b32_e32 v56, v57, v56, vcc
	v_mul_f32_e32 v57, v96, v54
	v_cmp_ne_u32_e32 vcc, s5, v101
	v_mul_f32_e32 v50, v56, v50
	v_mul_f32_e32 v56, v95, v55
	v_cndmask_b32_e32 v57, 2.0, v57, vcc
	v_cmp_lt_i32_e32 vcc, s5, v101
	s_movk_i32 s5, 0xc2
	v_add_u32_e32 v66, 0xffffff30, v101
	v_cndmask_b32_e32 v56, v57, v56, vcc
	v_mul_f32_e32 v57, v54, v94
	v_cmp_ne_u32_e32 vcc, s5, v101
	v_mul_f32_e32 v51, v56, v51
	v_mul_f32_e32 v56, v55, v93
	v_cndmask_b32_e32 v57, 2.0, v57, vcc
	v_cmp_lt_i32_e32 vcc, s5, v101
	s_movk_i32 s5, 0xc3
	v_mul_f32_e32 v54, v54, v92
	v_cndmask_b32_e32 v56, v57, v56, vcc
	v_cmp_ne_u32_e32 vcc, s5, v101
	v_mul_f32_e32 v55, v55, v91
	v_mul_f32_e32 v52, v56, v52
	v_cndmask_b32_e32 v54, 2.0, v54, vcc
	v_cmp_lt_i32_e32 vcc, s5, v101
	v_cvt_pk_bf16_f32 v50, v50, v51
	v_cvt_f32_i32_e32 v66, v66
	s_movk_i32 s5, 0xd0
	v_cndmask_b32_e32 v54, v54, v55, vcc
	v_mul_f32_e32 v53, v54, v53
	v_cvt_pk_bf16_f32 v51, v52, v53
	ds_write_b64 v100, v[50:51] offset:53248
	ds_read_b128 v[50:53], v83 offset:4352
	ds_read_b128 v[54:57], v83 offset:4416
	ds_read_b128 v[58:61], v83 offset:4480
	ds_read_b128 v[62:65], v83 offset:4544
	s_waitcnt lgkmcnt(3)
	v_mfma_f32_16x16x32_bf16 v[50:53], v[50:53], v[30:33], 0
	v_cmp_ne_u32_e32 vcc, s5, v101
	s_or_b32 s0, s1, s0
	s_add_i32 s0, s0, s3
	s_waitcnt lgkmcnt(2)
	v_mfma_f32_16x16x32_bf16 v[50:53], v[54:57], v[22:25], v[50:53]
	v_cvt_f32_i32_e32 v54, v67
	v_mul_f32_e32 v55, v90, v66
	v_exp_f32_e32 v55, v55
	s_waitcnt lgkmcnt(1)
	v_mfma_f32_16x16x32_bf16 v[50:53], v[58:61], v[14:17], v[50:53]
	v_mul_f32_e32 v54, v99, v54
	v_exp_f32_e32 v54, v54
	v_mul_f32_e32 v56, v55, v97
	s_waitcnt lgkmcnt(0)
	v_mfma_f32_16x16x32_bf16 v[50:53], v[62:65], v[10:13], v[50:53]
	v_sub_u32_e32 v67, 0xe0, v101
	v_mul_f32_e32 v57, v54, v98
	v_cndmask_b32_e32 v57, 2.0, v57, vcc
	v_cmp_lt_i32_e32 vcc, s5, v101
	s_movk_i32 s5, 0xd1
	v_add_u32_e32 v66, 0xffffff20, v101
	v_cndmask_b32_e32 v56, v57, v56, vcc
	v_mul_f32_e32 v57, v96, v54
	v_cmp_ne_u32_e32 vcc, s5, v101
	v_mul_f32_e32 v50, v56, v50
	v_mul_f32_e32 v56, v95, v55
	v_cndmask_b32_e32 v57, 2.0, v57, vcc
	v_cmp_lt_i32_e32 vcc, s5, v101
	s_movk_i32 s5, 0xd2
	v_cvt_f32_i32_e32 v66, v66
	v_cndmask_b32_e32 v56, v57, v56, vcc
	v_mul_f32_e32 v57, v54, v94
	v_cmp_ne_u32_e32 vcc, s5, v101
	v_mul_f32_e32 v51, v56, v51
	v_mul_f32_e32 v56, v55, v93
	v_cndmask_b32_e32 v57, 2.0, v57, vcc
	v_cmp_lt_i32_e32 vcc, s5, v101
	s_movk_i32 s5, 0xd3
	v_mul_f32_e32 v54, v54, v92
	v_cndmask_b32_e32 v56, v57, v56, vcc
	v_cmp_ne_u32_e32 vcc, s5, v101
	v_mul_f32_e32 v55, v55, v91
	v_mul_f32_e32 v52, v56, v52
	v_cndmask_b32_e32 v54, 2.0, v54, vcc
	v_cmp_lt_i32_e32 vcc, s5, v101
	v_cvt_pk_bf16_f32 v50, v50, v51
	s_movk_i32 s5, 0xe0
	s_mov_b32 s7, 0
	v_cndmask_b32_e32 v54, v54, v55, vcc
	v_mul_f32_e32 v53, v54, v53
	v_cvt_pk_bf16_f32 v51, v52, v53
	ds_write_b64 v100, v[50:51] offset:53280
	ds_read_b128 v[50:53], v83 offset:8704
	ds_read_b128 v[54:57], v83 offset:8768
	ds_read_b128 v[58:61], v83 offset:8832
	ds_read_b128 v[62:65], v83 offset:8896
	s_waitcnt lgkmcnt(3)
	v_mfma_f32_16x16x32_bf16 v[50:53], v[50:53], v[30:33], 0
	v_cmp_ne_u32_e32 vcc, s5, v101
	s_lshl_b32 s6, s4, 1
	s_waitcnt lgkmcnt(2)
	v_mfma_f32_16x16x32_bf16 v[50:53], v[54:57], v[22:25], v[50:53]
	v_cvt_f32_i32_e32 v54, v67
	v_mul_f32_e32 v55, v90, v66
	v_exp_f32_e32 v55, v55
	s_waitcnt lgkmcnt(1)
	v_mfma_f32_16x16x32_bf16 v[50:53], v[58:61], v[14:17], v[50:53]
	v_mul_f32_e32 v54, v99, v54
	v_exp_f32_e32 v54, v54
	v_mul_f32_e32 v56, v55, v97
	s_waitcnt lgkmcnt(0)
	v_mfma_f32_16x16x32_bf16 v[50:53], v[62:65], v[10:13], v[50:53]
	v_mul_f32_e32 v57, v54, v98
	v_cndmask_b32_e32 v57, 2.0, v57, vcc
	v_cmp_lt_i32_e32 vcc, s5, v101
	s_movk_i32 s5, 0xe1
	s_nop 0
	v_cndmask_b32_e32 v56, v57, v56, vcc
	v_mul_f32_e32 v57, v96, v54
	v_cmp_ne_u32_e32 vcc, s5, v101
	v_mul_f32_e32 v50, v56, v50
	v_mul_f32_e32 v56, v95, v55
	v_cndmask_b32_e32 v57, 2.0, v57, vcc
	v_cmp_lt_i32_e32 vcc, s5, v101
	s_movk_i32 s5, 0xe2
	s_nop 0
	v_cndmask_b32_e32 v56, v57, v56, vcc
	v_mul_f32_e32 v57, v54, v94
	v_cmp_ne_u32_e32 vcc, s5, v101
	v_mul_f32_e32 v51, v56, v51
	v_mul_f32_e32 v56, v55, v93
	v_cndmask_b32_e32 v57, 2.0, v57, vcc
	v_cmp_lt_i32_e32 vcc, s5, v101
	s_movk_i32 s5, 0xe3
	v_mul_f32_e32 v54, v54, v92
	v_cndmask_b32_e32 v56, v57, v56, vcc
	v_cmp_ne_u32_e32 vcc, s5, v101
	v_mul_f32_e32 v55, v55, v91
	v_mul_f32_e32 v52, v56, v52
	v_cndmask_b32_e32 v54, 2.0, v54, vcc
	v_cmp_lt_i32_e32 vcc, s5, v101
	v_cvt_pk_bf16_f32 v50, v50, v51
	s_movk_i32 s5, 0xf0
	s_nop 0
	v_cndmask_b32_e32 v54, v54, v55, vcc
	v_mul_f32_e32 v53, v54, v53
	v_cvt_pk_bf16_f32 v51, v52, v53
	ds_write_b64 v100, v[50:51] offset:53312
	ds_read_b128 v[50:53], v83 offset:13056
	ds_read_b128 v[54:57], v83 offset:13120
	ds_read_b128 v[58:61], v83 offset:13184
	ds_read_b128 v[62:65], v83 offset:13248
	s_waitcnt lgkmcnt(3)
	v_mfma_f32_16x16x32_bf16 v[30:33], v[50:53], v[30:33], 0
	v_sub_u32_e32 v51, 0xf0, v101
	v_add_u32_e32 v50, 0xffffff10, v101
	v_cvt_f32_i32_e32 v50, v50
	s_waitcnt lgkmcnt(2)
	v_mfma_f32_16x16x32_bf16 v[22:25], v[54:57], v[22:25], v[30:33]
	v_cmp_ne_u32_e32 vcc, s5, v101
	s_nop 1
	v_cvt_f32_i32_e32 v30, v51
	s_waitcnt lgkmcnt(1)
	v_mfma_f32_16x16x32_bf16 v[14:17], v[58:61], v[14:17], v[22:25]
	v_mul_f32_e32 v31, v90, v50
	v_mul_f32_e32 v30, v99, v30
	s_nop 0
	v_exp_f32_e32 v23, v30
	v_exp_f32_e32 v22, v31
	s_waitcnt lgkmcnt(0)
	v_mfma_f32_16x16x32_bf16 v[10:13], v[62:65], v[10:13], v[14:17]
	s_nop 2
	v_mul_f32_e32 v15, v23, v98
	v_mul_f32_e32 v14, v22, v97
	v_cndmask_b32_e32 v15, 2.0, v15, vcc
	v_cmp_lt_i32_e32 vcc, s5, v101
	s_movk_i32 s5, 0xf1
	s_nop 0
	v_cndmask_b32_e32 v14, v15, v14, vcc
	v_mul_f32_e32 v15, v96, v23
	v_cmp_ne_u32_e32 vcc, s5, v101
	v_mul_f32_e32 v10, v14, v10
	v_mul_f32_e32 v14, v95, v22
	v_cndmask_b32_e32 v15, 2.0, v15, vcc
	v_cmp_lt_i32_e32 vcc, s5, v101
	s_movk_i32 s5, 0xf2
	s_nop 0
	v_cndmask_b32_e32 v14, v15, v14, vcc
	v_mul_f32_e32 v15, v23, v94
	v_cmp_ne_u32_e32 vcc, s5, v101
	v_mul_f32_e32 v11, v14, v11
	v_mul_f32_e32 v14, v22, v93
	v_cndmask_b32_e32 v15, 2.0, v15, vcc
	v_cmp_lt_i32_e32 vcc, s5, v101
	s_movk_i32 s5, 0xf3
	v_cvt_pk_bf16_f32 v10, v10, v11
	s_nop 0
	v_cndmask_b32_e32 v14, v15, v14, vcc
	v_mul_f32_e32 v15, v23, v92
	v_cmp_ne_u32_e32 vcc, s5, v101
	v_mul_f32_e32 v12, v14, v12
	v_mul_f32_e32 v14, v22, v91
	v_cndmask_b32_e32 v15, 2.0, v15, vcc
	v_cmp_lt_i32_e32 vcc, s5, v101
	s_nop 1
	v_cndmask_b32_e32 v14, v15, v14, vcc
	v_mul_f32_e32 v13, v14, v13
	v_cvt_pk_bf16_f32 v11, v12, v13
	ds_write_b64 v100, v[10:11] offset:53344
	s_waitcnt lgkmcnt(0)
	ds_read_b128 v[54:57], v79 offset:53248
	ds_read_b128 v[50:53], v79 offset:53312
	ds_read_b64_tr_b16 v[12:13], v81 offset:18496
	ds_read_b64_tr_b16 v[10:11], v81 offset:17408
	ds_read_b64_tr_b16 v[14:15], v81 offset:17440
	ds_read_b64_tr_b16 v[58:59], v81 offset:17472
	ds_read_b64_tr_b16 v[62:63], v81 offset:17504
	ds_read_b64_tr_b16 v[16:17], v81 offset:18528
	ds_read_b64_tr_b16 v[60:61], v81 offset:18560
	ds_read_b64_tr_b16 v[64:65], v81 offset:18592
	s_waitcnt lgkmcnt(6)
	v_mfma_f32_16x16x32_bf16 v[10:13], v[54:57], v[10:13], v[46:49]
	ds_read_b64_tr_b16 v[24:25], v81 offset:27200
	ds_read_b64_tr_b16 v[22:23], v81 offset:26112
	s_nop 0
	ds_read_b64_tr_b16 v[46:47], v81 offset:26144
	ds_read_b64_tr_b16 v[66:67], v81 offset:26176
	ds_read_b64_tr_b16 v[70:71], v81 offset:26208
	ds_read_b64_tr_b16 v[48:49], v81 offset:27232
	ds_read_b64_tr_b16 v[68:69], v81 offset:27264
	ds_read_b64_tr_b16 v[72:73], v81 offset:27296
	s_waitcnt lgkmcnt(6)
	v_mfma_f32_16x16x32_bf16 v[30:33], v[50:53], v[22:25], v[10:13]
	v_mfma_f32_16x16x32_bf16 v[10:13], v[54:57], v[14:17], v[42:45]
	s_waitcnt lgkmcnt(2)
	v_mfma_f32_16x16x32_bf16 v[22:25], v[50:53], v[46:49], v[10:13]
	v_mfma_f32_16x16x32_bf16 v[10:13], v[54:57], v[58:61], v[38:41]
	s_waitcnt lgkmcnt(1)
	v_mfma_f32_16x16x32_bf16 v[14:17], v[50:53], v[66:69], v[10:13]
	v_mfma_f32_16x16x32_bf16 v[10:13], v[54:57], v[62:65], v[34:37]
	s_nop 2
	ds_read_b64_tr_b16 v[36:37], v81 offset:18624
	ds_read_b64_tr_b16 v[34:35], v81 offset:17536
	ds_read_b64_tr_b16 v[38:39], v81 offset:17568
	ds_read_b64_tr_b16 v[42:43], v81 offset:17600
	ds_read_b64_tr_b16 v[46:47], v81 offset:17632
	ds_read_b64_tr_b16 v[40:41], v81 offset:18656
	ds_read_b64_tr_b16 v[44:45], v81 offset:18688
	ds_read_b64_tr_b16 v[48:49], v81 offset:18720
	s_waitcnt lgkmcnt(6)
	v_mfma_f32_16x16x32_bf16 v[26:29], v[54:57], v[34:37], v[26:29]
	ds_read_b64_tr_b16 v[36:37], v81 offset:27328
	ds_read_b64_tr_b16 v[34:35], v81 offset:26240
	ds_read_b64_tr_b16 v[58:59], v81 offset:26272
	ds_read_b64_tr_b16 v[62:63], v81 offset:26304
	ds_read_b64_tr_b16 v[66:67], v81 offset:26336
	ds_read_b64_tr_b16 v[60:61], v81 offset:27360
	ds_read_b64_tr_b16 v[64:65], v81 offset:27392
	ds_read_b64_tr_b16 v[68:69], v81 offset:27424
	s_waitcnt lgkmcnt(6)
	v_mfma_f32_16x16x32_bf16 v[26:29], v[50:53], v[34:37], v[26:29]
	v_and_b32_e32 v34, 15, v1
	v_ashrrev_i32_e32 v1, 2, v1
	v_and_b32_e32 v1, -4, v1
	v_mfma_f32_16x16x32_bf16 v[18:21], v[54:57], v[38:41], v[18:21]
	v_add_u32_e32 v36, s0, v1
	s_movk_i32 s0, 0x1400
	v_mov_b64_e32 v[40:41], s[68:69]
	v_lshlrev_b32_e32 v38, 1, v34
	v_mad_i64_i32 v[34:35], s[4:5], v36, s0, v[40:41]
	v_mov_b32_e32 v39, 0
	v_lshl_add_u64 v[34:35], v[34:35], 0, s[6:7]
	s_waitcnt lgkmcnt(2)
	v_mfma_f32_16x16x32_bf16 v[18:21], v[50:53], v[58:61], v[18:21]
	v_lshl_add_u64 v[58:59], v[34:35], 0, v[38:39]
	v_add_f32_e32 v1, 0, v30
	v_mfma_f32_16x16x32_bf16 v[2:5], v[54:57], v[42:45], v[2:5]
	v_add_f32_e32 v1, v1, v22
	v_mfma_f32_16x16x32_bf16 v[6:9], v[54:57], v[46:49], v[6:9]
	v_mfma_f32_16x16x32_bf16 v[10:13], v[50:53], v[70:73], v[10:13]
	v_add_f32_e32 v1, v1, v14
	s_add_u32 s4, s60, s6
	s_addc_u32 s5, s61, 0
	s_waitcnt lgkmcnt(1)
	v_mfma_f32_16x16x32_bf16 v[2:5], v[50:53], v[62:65], v[2:5]
	v_lshl_add_u64 v[34:35], s[4:5], 0, v[38:39]
	s_nop 1
	v_add_f32_e32 v1, v1, v10
	v_add_f32_e32 v1, v1, v26
	s_waitcnt lgkmcnt(0)
	v_mfma_f32_16x16x32_bf16 v[6:9], v[50:53], v[66:69], v[6:9]
	s_nop 7
	s_nop 7
	s_nop 3
	v_and_b32_e32 v160, 63, v0
	v_and_b32_e32 v161, 15, v160
	v_lshrrev_b32_e32 v162, 4, v160
	v_mov_b32_e32 v163, 0x3727c5ac
	v_add_f32_e32 v164, 0, v30
	v_add_f32_e32 v164, v164, v22
	v_add_f32_e32 v164, v164, v14
	v_add_f32_e32 v164, v164, v10
	v_add_f32_e32 v164, v164, v26
	v_add_f32_e32 v164, v164, v18
	v_add_f32_e32 v164, v164, v2
	v_add_f32_e32 v164, v164, v6
	s_nop 1
	v_add_f32_dpp v164, v164, v164 quad_perm:[1,0,3,2] row_mask:0xf bank_mask:0xf bound_ctrl:1
	s_nop 1
	v_add_f32_dpp v164, v164, v164 quad_perm:[2,3,0,1] row_mask:0xf bank_mask:0xf bound_ctrl:1
	s_nop 1
	v_add_f32_dpp v164, v164, v164 row_half_mirror row_mask:0xf bank_mask:0xf bound_ctrl:1
	s_nop 1
	v_add_f32_dpp v164, v164, v164 row_mirror row_mask:0xf bank_mask:0xf bound_ctrl:1
	v_fmamk_f32 v22, v164, 0xbc000000, v22
	v_fmamk_f32 v30, v164, 0xbc000000, v30
	v_mul_f32_e32 v165, v22, v22
	v_fmac_f32_e32 v165, v30, v30
	v_fmamk_f32 v14, v164, 0xbc000000, v14
	v_fmac_f32_e32 v165, v14, v14
	v_fmamk_f32 v10, v164, 0xbc000000, v10
	v_fmac_f32_e32 v165, v10, v10
	v_fmamk_f32 v26, v164, 0xbc000000, v26
	v_fmac_f32_e32 v165, v26, v26
	v_fmamk_f32 v18, v164, 0xbc000000, v18
	v_fmac_f32_e32 v165, v18, v18
	v_fmamk_f32 v2, v164, 0xbc000000, v2
	v_fmac_f32_e32 v165, v2, v2
	v_fmamk_f32 v6, v164, 0xbc000000, v6
	v_fmac_f32_e32 v165, v6, v6
	s_nop 1
	v_add_f32_dpp v165, v165, v165 quad_perm:[1,0,3,2] row_mask:0xf bank_mask:0xf bound_ctrl:1
	s_nop 1
	v_add_f32_dpp v165, v165, v165 quad_perm:[2,3,0,1] row_mask:0xf bank_mask:0xf bound_ctrl:1
	s_nop 1
	v_add_f32_dpp v165, v165, v165 row_half_mirror row_mask:0xf bank_mask:0xf bound_ctrl:1
	s_nop 1
	v_add_f32_dpp v165, v165, v165 row_mirror row_mask:0xf bank_mask:0xf bound_ctrl:1
	v_fmamk_f32 v165, v165, 0x3c000000, v163
	v_rsq_f32_e32 v165, v165
	s_nop 0
	v_mul_f32_e32 v30, v30, v165
	v_mul_f32_e32 v22, v22, v165
	v_mul_f32_e32 v14, v14, v165
	v_mul_f32_e32 v10, v10, v165
	v_mul_f32_e32 v26, v26, v165
	v_mul_f32_e32 v18, v18, v165
	v_mul_f32_e32 v2, v2, v165
	v_mul_f32_e32 v6, v6, v165
	v_add_f32_e32 v164, 0, v31
	v_add_f32_e32 v164, v164, v23
	v_add_f32_e32 v164, v164, v15
	v_add_f32_e32 v164, v164, v11
	v_add_f32_e32 v164, v164, v27
	v_add_f32_e32 v164, v164, v19
	v_add_f32_e32 v164, v164, v3
	v_add_f32_e32 v164, v164, v7
	s_nop 1
	v_add_f32_dpp v164, v164, v164 quad_perm:[1,0,3,2] row_mask:0xf bank_mask:0xf bound_ctrl:1
	s_nop 1
	v_add_f32_dpp v164, v164, v164 quad_perm:[2,3,0,1] row_mask:0xf bank_mask:0xf bound_ctrl:1
	s_nop 1
	v_add_f32_dpp v164, v164, v164 row_half_mirror row_mask:0xf bank_mask:0xf bound_ctrl:1
	s_nop 1
	v_add_f32_dpp v164, v164, v164 row_mirror row_mask:0xf bank_mask:0xf bound_ctrl:1
	v_fmamk_f32 v23, v164, 0xbc000000, v23
	v_fmamk_f32 v31, v164, 0xbc000000, v31
	v_mul_f32_e32 v165, v23, v23
	v_fmac_f32_e32 v165, v31, v31
	v_fmamk_f32 v15, v164, 0xbc000000, v15
	v_fmac_f32_e32 v165, v15, v15
	v_fmamk_f32 v11, v164, 0xbc000000, v11
	v_fmac_f32_e32 v165, v11, v11
	v_fmamk_f32 v27, v164, 0xbc000000, v27
	v_fmac_f32_e32 v165, v27, v27
	v_fmamk_f32 v19, v164, 0xbc000000, v19
	v_fmac_f32_e32 v165, v19, v19
	v_fmamk_f32 v3, v164, 0xbc000000, v3
	v_fmac_f32_e32 v165, v3, v3
	v_fmamk_f32 v7, v164, 0xbc000000, v7
	v_fmac_f32_e32 v165, v7, v7
	s_nop 1
	v_add_f32_dpp v165, v165, v165 quad_perm:[1,0,3,2] row_mask:0xf bank_mask:0xf bound_ctrl:1
	s_nop 1
	v_add_f32_dpp v165, v165, v165 quad_perm:[2,3,0,1] row_mask:0xf bank_mask:0xf bound_ctrl:1
	s_nop 1
	v_add_f32_dpp v165, v165, v165 row_half_mirror row_mask:0xf bank_mask:0xf bound_ctrl:1
	s_nop 1
	v_add_f32_dpp v165, v165, v165 row_mirror row_mask:0xf bank_mask:0xf bound_ctrl:1
	v_fmamk_f32 v165, v165, 0x3c000000, v163
	v_rsq_f32_e32 v165, v165
	s_nop 0
	v_mul_f32_e32 v31, v31, v165
	v_mul_f32_e32 v23, v23, v165
	v_mul_f32_e32 v15, v15, v165
	v_mul_f32_e32 v11, v11, v165
	v_mul_f32_e32 v27, v27, v165
	v_mul_f32_e32 v19, v19, v165
	v_mul_f32_e32 v3, v3, v165
	v_mul_f32_e32 v7, v7, v165
	v_add_f32_e32 v164, 0, v32
	v_add_f32_e32 v164, v164, v24
	v_add_f32_e32 v164, v164, v16
	v_add_f32_e32 v164, v164, v12
	v_add_f32_e32 v164, v164, v28
	v_add_f32_e32 v164, v164, v20
	v_add_f32_e32 v164, v164, v4
	v_add_f32_e32 v164, v164, v8
	s_nop 1
	v_add_f32_dpp v164, v164, v164 quad_perm:[1,0,3,2] row_mask:0xf bank_mask:0xf bound_ctrl:1
	s_nop 1
	v_add_f32_dpp v164, v164, v164 quad_perm:[2,3,0,1] row_mask:0xf bank_mask:0xf bound_ctrl:1
	s_nop 1
	v_add_f32_dpp v164, v164, v164 row_half_mirror row_mask:0xf bank_mask:0xf bound_ctrl:1
	s_nop 1
	v_add_f32_dpp v164, v164, v164 row_mirror row_mask:0xf bank_mask:0xf bound_ctrl:1
	v_fmamk_f32 v24, v164, 0xbc000000, v24
	v_fmamk_f32 v32, v164, 0xbc000000, v32
	v_mul_f32_e32 v165, v24, v24
	v_fmac_f32_e32 v165, v32, v32
	v_fmamk_f32 v16, v164, 0xbc000000, v16
	v_fmac_f32_e32 v165, v16, v16
	v_fmamk_f32 v12, v164, 0xbc000000, v12
	v_fmac_f32_e32 v165, v12, v12
	v_fmamk_f32 v28, v164, 0xbc000000, v28
	v_fmac_f32_e32 v165, v28, v28
	v_fmamk_f32 v20, v164, 0xbc000000, v20
	v_fmac_f32_e32 v165, v20, v20
	v_fmamk_f32 v4, v164, 0xbc000000, v4
	v_fmac_f32_e32 v165, v4, v4
	v_fmamk_f32 v8, v164, 0xbc000000, v8
	v_fmac_f32_e32 v165, v8, v8
	s_nop 1
	v_add_f32_dpp v165, v165, v165 quad_perm:[1,0,3,2] row_mask:0xf bank_mask:0xf bound_ctrl:1
	s_nop 1
	v_add_f32_dpp v165, v165, v165 quad_perm:[2,3,0,1] row_mask:0xf bank_mask:0xf bound_ctrl:1
	s_nop 1
	v_add_f32_dpp v165, v165, v165 row_half_mirror row_mask:0xf bank_mask:0xf bound_ctrl:1
	s_nop 1
	v_add_f32_dpp v165, v165, v165 row_mirror row_mask:0xf bank_mask:0xf bound_ctrl:1
	v_fmamk_f32 v165, v165, 0x3c000000, v163
	v_rsq_f32_e32 v165, v165
	s_nop 0
	v_mul_f32_e32 v32, v32, v165
	v_mul_f32_e32 v24, v24, v165
	v_mul_f32_e32 v16, v16, v165
	v_mul_f32_e32 v12, v12, v165
	v_mul_f32_e32 v28, v28, v165
	v_mul_f32_e32 v20, v20, v165
	v_mul_f32_e32 v4, v4, v165
	v_mul_f32_e32 v8, v8, v165
	v_add_f32_e32 v164, 0, v33
	v_add_f32_e32 v164, v164, v25
	v_add_f32_e32 v164, v164, v17
	v_add_f32_e32 v164, v164, v13
	v_add_f32_e32 v164, v164, v29
	v_add_f32_e32 v164, v164, v21
	v_add_f32_e32 v164, v164, v5
	v_add_f32_e32 v164, v164, v9
	s_nop 1
	v_add_f32_dpp v164, v164, v164 quad_perm:[1,0,3,2] row_mask:0xf bank_mask:0xf bound_ctrl:1
	s_nop 1
	v_add_f32_dpp v164, v164, v164 quad_perm:[2,3,0,1] row_mask:0xf bank_mask:0xf bound_ctrl:1
	s_nop 1
	v_add_f32_dpp v164, v164, v164 row_half_mirror row_mask:0xf bank_mask:0xf bound_ctrl:1
	s_nop 1
	v_add_f32_dpp v164, v164, v164 row_mirror row_mask:0xf bank_mask:0xf bound_ctrl:1
	v_fmamk_f32 v25, v164, 0xbc000000, v25
	v_fmamk_f32 v33, v164, 0xbc000000, v33
	v_mul_f32_e32 v165, v25, v25
	v_fmac_f32_e32 v165, v33, v33
	v_fmamk_f32 v17, v164, 0xbc000000, v17
	v_fmac_f32_e32 v165, v17, v17
	v_fmamk_f32 v13, v164, 0xbc000000, v13
	v_fmac_f32_e32 v165, v13, v13
	v_fmamk_f32 v29, v164, 0xbc000000, v29
	v_fmac_f32_e32 v165, v29, v29
	v_fmamk_f32 v21, v164, 0xbc000000, v21
	v_fmac_f32_e32 v165, v21, v21
	v_fmamk_f32 v5, v164, 0xbc000000, v5
	v_fmac_f32_e32 v165, v5, v5
	v_fmamk_f32 v9, v164, 0xbc000000, v9
	v_fmac_f32_e32 v165, v9, v9
	s_nop 1
	v_add_f32_dpp v165, v165, v165 quad_perm:[1,0,3,2] row_mask:0xf bank_mask:0xf bound_ctrl:1
	s_nop 1
	v_add_f32_dpp v165, v165, v165 quad_perm:[2,3,0,1] row_mask:0xf bank_mask:0xf bound_ctrl:1
	s_nop 1
	v_add_f32_dpp v165, v165, v165 row_half_mirror row_mask:0xf bank_mask:0xf bound_ctrl:1
	s_nop 1
	v_add_f32_dpp v165, v165, v165 row_mirror row_mask:0xf bank_mask:0xf bound_ctrl:1
	v_fmamk_f32 v165, v165, 0x3c000000, v163
	v_rsq_f32_e32 v165, v165
	s_nop 0
	v_mul_f32_e32 v33, v33, v165
	v_mul_f32_e32 v25, v25, v165
	v_mul_f32_e32 v17, v17, v165
	v_mul_f32_e32 v13, v13, v165
	v_mul_f32_e32 v29, v29, v165
	v_mul_f32_e32 v21, v21, v165
	v_mul_f32_e32 v5, v5, v165
	v_mul_f32_e32 v9, v9, v165
	v_readfirstlane_b32 s98, v0
	s_lshr_b32 s98, s98, 6
	s_mul_i32 s98, s98, 0x1200
	s_add_i32 s98, s98, 0xd000
	v_lshlrev_b32_e32 v167, 2, v162
	v_mul_u32_u24_e32 v167, 0x110, v167
	v_lshl_add_u32 v167, v161, 2, v167
	v_add_u32_e32 v167, s98, v167
	v_lshrrev_b32_e32 v168, 2, v160
	v_and_b32_e32 v169, 3, v160
	v_mul_u32_u24_e32 v170, 0x110, v168
	v_lshl_add_u32 v170, v169, 6, v170
	v_add_u32_e32 v170, s98, v170
	v_readfirstlane_b32 s99, v36
	v_add_u32_e32 v171, s99, v168
	v_mul_u32_u24_e32 v172, 0x1400, v171
	v_lshl_add_u32 v172, v169, 5, v172
	v_add_u32_e32 v172, 0xc00, v172
	v_lshlrev_b32_e32 v173, 11, v171
	v_lshl_add_u32 v173, v169, 5, v173
	s_add_u32 s100, s68, s6
	s_addc_u32 s101, s69, 0
	ds_write_b32 v167, v30
	ds_write_b32 v167, v22 offset:64
	ds_write_b32 v167, v14 offset:128
	ds_write_b32 v167, v10 offset:192
	ds_write_b32 v167, v31 offset:272
	ds_write_b32 v167, v23 offset:336
	ds_write_b32 v167, v15 offset:400
	ds_write_b32 v167, v11 offset:464
	ds_write_b32 v167, v32 offset:544
	ds_write_b32 v167, v24 offset:608
	ds_write_b32 v167, v16 offset:672
	ds_write_b32 v167, v12 offset:736
	ds_write_b32 v167, v33 offset:816
	ds_write_b32 v167, v25 offset:880
	ds_write_b32 v167, v17 offset:944
	ds_write_b32 v167, v13 offset:1008
	s_waitcnt lgkmcnt(0)
	ds_read_b128 v[184:187], v170
	ds_read_b128 v[188:191], v170 offset:16
	ds_read_b128 v[192:195], v170 offset:32
	ds_read_b128 v[196:199], v170 offset:48
	global_load_dwordx4 v[200:203], v172, s[100:101]
	global_load_dwordx4 v[204:207], v172, s[100:101] offset:16
	s_waitcnt vmcnt(0) lgkmcnt(0)
	v_lshlrev_b32_e32 v220, 16, v200
	v_and_b32_e32 v221, 0xffff0000, v200
	v_mul_f32_e32 v222, 0xbfb8aa3b, v220
	v_mul_f32_e32 v223, 0xbfb8aa3b, v221
	v_exp_f32_e32 v222, v222
	v_exp_f32_e32 v223, v223
	s_nop 0
	v_add_f32_e32 v222, 1.0, v222
	v_add_f32_e32 v223, 1.0, v223
	v_rcp_f32_e32 v222, v222
	v_rcp_f32_e32 v223, v223
	s_nop 0
	v_mul_f32_e32 v220, v222, v220
	v_mul_f32_e32 v221, v223, v221
	v_mul_f32_e32 v220, v220, v184
	v_mul_f32_e32 v221, v221, v185
	v_cvt_pk_bf16_f32 v208, v220, v221
	v_lshlrev_b32_e32 v220, 16, v201
	v_and_b32_e32 v221, 0xffff0000, v201
	v_mul_f32_e32 v222, 0xbfb8aa3b, v220
	v_mul_f32_e32 v223, 0xbfb8aa3b, v221
	v_exp_f32_e32 v222, v222
	v_exp_f32_e32 v223, v223
	s_nop 0
	v_add_f32_e32 v222, 1.0, v222
	v_add_f32_e32 v223, 1.0, v223
	v_rcp_f32_e32 v222, v222
	v_rcp_f32_e32 v223, v223
	s_nop 0
	v_mul_f32_e32 v220, v222, v220
	v_mul_f32_e32 v221, v223, v221
	v_mul_f32_e32 v220, v220, v186
	v_mul_f32_e32 v221, v221, v187
	v_cvt_pk_bf16_f32 v209, v220, v221
	v_lshlrev_b32_e32 v220, 16, v202
	v_and_b32_e32 v221, 0xffff0000, v202
	v_mul_f32_e32 v222, 0xbfb8aa3b, v220
	v_mul_f32_e32 v223, 0xbfb8aa3b, v221
	v_exp_f32_e32 v222, v222
	v_exp_f32_e32 v223, v223
	s_nop 0
	v_add_f32_e32 v222, 1.0, v222
	v_add_f32_e32 v223, 1.0, v223
	v_rcp_f32_e32 v222, v222
	v_rcp_f32_e32 v223, v223
	s_nop 0
	v_mul_f32_e32 v220, v222, v220
	v_mul_f32_e32 v221, v223, v221
	v_mul_f32_e32 v220, v220, v188
	v_mul_f32_e32 v221, v221, v189
	v_cvt_pk_bf16_f32 v210, v220, v221
	v_lshlrev_b32_e32 v220, 16, v203
	v_and_b32_e32 v221, 0xffff0000, v203
	v_mul_f32_e32 v222, 0xbfb8aa3b, v220
	v_mul_f32_e32 v223, 0xbfb8aa3b, v221
	v_exp_f32_e32 v222, v222
	v_exp_f32_e32 v223, v223
	s_nop 0
	v_add_f32_e32 v222, 1.0, v222
	v_add_f32_e32 v223, 1.0, v223
	v_rcp_f32_e32 v222, v222
	v_rcp_f32_e32 v223, v223
	s_nop 0
	v_mul_f32_e32 v220, v222, v220
	v_mul_f32_e32 v221, v223, v221
	v_mul_f32_e32 v220, v220, v190
	v_mul_f32_e32 v221, v221, v191
	v_cvt_pk_bf16_f32 v211, v220, v221
	v_lshlrev_b32_e32 v220, 16, v204
	v_and_b32_e32 v221, 0xffff0000, v204
	v_mul_f32_e32 v222, 0xbfb8aa3b, v220
	v_mul_f32_e32 v223, 0xbfb8aa3b, v221
	v_exp_f32_e32 v222, v222
	v_exp_f32_e32 v223, v223
	s_nop 0
	v_add_f32_e32 v222, 1.0, v222
	v_add_f32_e32 v223, 1.0, v223
	v_rcp_f32_e32 v222, v222
	v_rcp_f32_e32 v223, v223
	s_nop 0
	v_mul_f32_e32 v220, v222, v220
	v_mul_f32_e32 v221, v223, v221
	v_mul_f32_e32 v220, v220, v192
	v_mul_f32_e32 v221, v221, v193
	v_cvt_pk_bf16_f32 v216, v220, v221
	v_lshlrev_b32_e32 v220, 16, v205
	v_and_b32_e32 v221, 0xffff0000, v205
	v_mul_f32_e32 v222, 0xbfb8aa3b, v220
	v_mul_f32_e32 v223, 0xbfb8aa3b, v221
	v_exp_f32_e32 v222, v222
	v_exp_f32_e32 v223, v223
	s_nop 0
	v_add_f32_e32 v222, 1.0, v222
	v_add_f32_e32 v223, 1.0, v223
	v_rcp_f32_e32 v222, v222
	v_rcp_f32_e32 v223, v223
	s_nop 0
	v_mul_f32_e32 v220, v222, v220
	v_mul_f32_e32 v221, v223, v221
	v_mul_f32_e32 v220, v220, v194
	v_mul_f32_e32 v221, v221, v195
	v_cvt_pk_bf16_f32 v217, v220, v221
	v_lshlrev_b32_e32 v220, 16, v206
	v_and_b32_e32 v221, 0xffff0000, v206
	v_mul_f32_e32 v222, 0xbfb8aa3b, v220
	v_mul_f32_e32 v223, 0xbfb8aa3b, v221
	v_exp_f32_e32 v222, v222
	v_exp_f32_e32 v223, v223
	s_nop 0
	v_add_f32_e32 v222, 1.0, v222
	v_add_f32_e32 v223, 1.0, v223
	v_rcp_f32_e32 v222, v222
	v_rcp_f32_e32 v223, v223
	s_nop 0
	v_mul_f32_e32 v220, v222, v220
	v_mul_f32_e32 v221, v223, v221
	v_mul_f32_e32 v220, v220, v196
	v_mul_f32_e32 v221, v221, v197
	v_cvt_pk_bf16_f32 v218, v220, v221
	v_lshlrev_b32_e32 v220, 16, v207
	v_and_b32_e32 v221, 0xffff0000, v207
	v_mul_f32_e32 v222, 0xbfb8aa3b, v220
	v_mul_f32_e32 v223, 0xbfb8aa3b, v221
	v_exp_f32_e32 v222, v222
	v_exp_f32_e32 v223, v223
	s_nop 0
	v_add_f32_e32 v222, 1.0, v222
	v_add_f32_e32 v223, 1.0, v223
	v_rcp_f32_e32 v222, v222
	v_rcp_f32_e32 v223, v223
	s_nop 0
	v_mul_f32_e32 v220, v222, v220
	v_mul_f32_e32 v221, v223, v221
	v_mul_f32_e32 v220, v220, v198
	v_mul_f32_e32 v221, v221, v199
	v_cvt_pk_bf16_f32 v219, v220, v221
	global_store_dwordx4 v173, v[208:211], s[4:5]
	global_store_dwordx4 v173, v[216:219], s[4:5] offset:16
	ds_write_b32 v167, v26
	ds_write_b32 v167, v18 offset:64
	ds_write_b32 v167, v2 offset:128
	ds_write_b32 v167, v6 offset:192
	ds_write_b32 v167, v27 offset:272
	ds_write_b32 v167, v19 offset:336
	ds_write_b32 v167, v3 offset:400
	ds_write_b32 v167, v7 offset:464
	ds_write_b32 v167, v28 offset:544
	ds_write_b32 v167, v20 offset:608
	ds_write_b32 v167, v4 offset:672
	ds_write_b32 v167, v8 offset:736
	ds_write_b32 v167, v29 offset:816
	ds_write_b32 v167, v21 offset:880
	ds_write_b32 v167, v5 offset:944
	ds_write_b32 v167, v9 offset:1008
	s_waitcnt lgkmcnt(0)
	ds_read_b128 v[184:187], v170
	ds_read_b128 v[188:191], v170 offset:16
	ds_read_b128 v[192:195], v170 offset:32
	ds_read_b128 v[196:199], v170 offset:48
	global_load_dwordx4 v[200:203], v172, s[100:101] offset:128
	global_load_dwordx4 v[204:207], v172, s[100:101] offset:144
	s_waitcnt vmcnt(0) lgkmcnt(0)
	v_lshlrev_b32_e32 v220, 16, v200
	v_and_b32_e32 v221, 0xffff0000, v200
	v_mul_f32_e32 v222, 0xbfb8aa3b, v220
	v_mul_f32_e32 v223, 0xbfb8aa3b, v221
	v_exp_f32_e32 v222, v222
	v_exp_f32_e32 v223, v223
	s_nop 0
	v_add_f32_e32 v222, 1.0, v222
	v_add_f32_e32 v223, 1.0, v223
	v_rcp_f32_e32 v222, v222
	v_rcp_f32_e32 v223, v223
	s_nop 0
	v_mul_f32_e32 v220, v222, v220
	v_mul_f32_e32 v221, v223, v221
	v_mul_f32_e32 v220, v220, v184
	v_mul_f32_e32 v221, v221, v185
	v_cvt_pk_bf16_f32 v208, v220, v221
	v_lshlrev_b32_e32 v220, 16, v201
	v_and_b32_e32 v221, 0xffff0000, v201
	v_mul_f32_e32 v222, 0xbfb8aa3b, v220
	v_mul_f32_e32 v223, 0xbfb8aa3b, v221
	v_exp_f32_e32 v222, v222
	v_exp_f32_e32 v223, v223
	s_nop 0
	v_add_f32_e32 v222, 1.0, v222
	v_add_f32_e32 v223, 1.0, v223
	v_rcp_f32_e32 v222, v222
	v_rcp_f32_e32 v223, v223
	s_nop 0
	v_mul_f32_e32 v220, v222, v220
	v_mul_f32_e32 v221, v223, v221
	v_mul_f32_e32 v220, v220, v186
	v_mul_f32_e32 v221, v221, v187
	v_cvt_pk_bf16_f32 v209, v220, v221
	v_lshlrev_b32_e32 v220, 16, v202
	v_and_b32_e32 v221, 0xffff0000, v202
	v_mul_f32_e32 v222, 0xbfb8aa3b, v220
	v_mul_f32_e32 v223, 0xbfb8aa3b, v221
	v_exp_f32_e32 v222, v222
	v_exp_f32_e32 v223, v223
	s_nop 0
	v_add_f32_e32 v222, 1.0, v222
	v_add_f32_e32 v223, 1.0, v223
	v_rcp_f32_e32 v222, v222
	v_rcp_f32_e32 v223, v223
	s_nop 0
	v_mul_f32_e32 v220, v222, v220
	v_mul_f32_e32 v221, v223, v221
	v_mul_f32_e32 v220, v220, v188
	v_mul_f32_e32 v221, v221, v189
	v_cvt_pk_bf16_f32 v210, v220, v221
	v_lshlrev_b32_e32 v220, 16, v203
	v_and_b32_e32 v221, 0xffff0000, v203
	v_mul_f32_e32 v222, 0xbfb8aa3b, v220
	v_mul_f32_e32 v223, 0xbfb8aa3b, v221
	v_exp_f32_e32 v222, v222
	v_exp_f32_e32 v223, v223
	s_nop 0
	v_add_f32_e32 v222, 1.0, v222
	v_add_f32_e32 v223, 1.0, v223
	v_rcp_f32_e32 v222, v222
	v_rcp_f32_e32 v223, v223
	s_nop 0
	v_mul_f32_e32 v220, v222, v220
	v_mul_f32_e32 v221, v223, v221
	v_mul_f32_e32 v220, v220, v190
	v_mul_f32_e32 v221, v221, v191
	v_cvt_pk_bf16_f32 v211, v220, v221
	v_lshlrev_b32_e32 v220, 16, v204
	v_and_b32_e32 v221, 0xffff0000, v204
	v_mul_f32_e32 v222, 0xbfb8aa3b, v220
	v_mul_f32_e32 v223, 0xbfb8aa3b, v221
	v_exp_f32_e32 v222, v222
	v_exp_f32_e32 v223, v223
	s_nop 0
	v_add_f32_e32 v222, 1.0, v222
	v_add_f32_e32 v223, 1.0, v223
	v_rcp_f32_e32 v222, v222
	v_rcp_f32_e32 v223, v223
	s_nop 0
	v_mul_f32_e32 v220, v222, v220
	v_mul_f32_e32 v221, v223, v221
	v_mul_f32_e32 v220, v220, v192
	v_mul_f32_e32 v221, v221, v193
	v_cvt_pk_bf16_f32 v216, v220, v221
	v_lshlrev_b32_e32 v220, 16, v205
	v_and_b32_e32 v221, 0xffff0000, v205
	v_mul_f32_e32 v222, 0xbfb8aa3b, v220
	v_mul_f32_e32 v223, 0xbfb8aa3b, v221
	v_exp_f32_e32 v222, v222
	v_exp_f32_e32 v223, v223
	s_nop 0
	v_add_f32_e32 v222, 1.0, v222
	v_add_f32_e32 v223, 1.0, v223
	v_rcp_f32_e32 v222, v222
	v_rcp_f32_e32 v223, v223
	s_nop 0
	v_mul_f32_e32 v220, v222, v220
	v_mul_f32_e32 v221, v223, v221
	v_mul_f32_e32 v220, v220, v194
	v_mul_f32_e32 v221, v221, v195
	v_cvt_pk_bf16_f32 v217, v220, v221
	v_lshlrev_b32_e32 v220, 16, v206
	v_and_b32_e32 v221, 0xffff0000, v206
	v_mul_f32_e32 v222, 0xbfb8aa3b, v220
	v_mul_f32_e32 v223, 0xbfb8aa3b, v221
	v_exp_f32_e32 v222, v222
	v_exp_f32_e32 v223, v223
	s_nop 0
	v_add_f32_e32 v222, 1.0, v222
	v_add_f32_e32 v223, 1.0, v223
	v_rcp_f32_e32 v222, v222
	v_rcp_f32_e32 v223, v223
	s_nop 0
	v_mul_f32_e32 v220, v222, v220
	v_mul_f32_e32 v221, v223, v221
	v_mul_f32_e32 v220, v220, v196
	v_mul_f32_e32 v221, v221, v197
	v_cvt_pk_bf16_f32 v218, v220, v221
	v_lshlrev_b32_e32 v220, 16, v207
	v_and_b32_e32 v221, 0xffff0000, v207
	v_mul_f32_e32 v222, 0xbfb8aa3b, v220
	v_mul_f32_e32 v223, 0xbfb8aa3b, v221
	v_exp_f32_e32 v222, v222
	v_exp_f32_e32 v223, v223
	s_nop 0
	v_add_f32_e32 v222, 1.0, v222
	v_add_f32_e32 v223, 1.0, v223
	v_rcp_f32_e32 v222, v222
	v_rcp_f32_e32 v223, v223
	s_nop 0
	v_mul_f32_e32 v220, v222, v220
	v_mul_f32_e32 v221, v223, v221
	v_mul_f32_e32 v220, v220, v198
	v_mul_f32_e32 v221, v221, v199
	v_cvt_pk_bf16_f32 v219, v220, v221
	global_store_dwordx4 v173, v[208:211], s[4:5] offset:128
	global_store_dwordx4 v173, v[216:219], s[4:5] offset:144
